# attention loops: LDS-DMA m0 and global address stepping moved from VALU to SALU (saddr-form loads, hoisted per-wave LDS base)
# speedup vs baseline: 1.0313x; 1.0203x over previous
; template <int DQK, bool MIXA, bool PIPE>
; DI void attn_item(const Params& P, int layer, char* smem, int b, int h, int qt) {
;     ...
;     for (int i = 0; i < DQK; ++i) { a1 = fmaxf(a1, fabsf(g1[i])); a2 = fmaxf(a2, fabsf(g2[i])); }
;     mfix = (float)DQK * 1.02f * a1 * a2 * sl2;
;     if (MIXA) {
;       const float b15 = P.rel_bias[15 * 8 + h];
;       float bm = 0.f;
;       for (int i = 0; i < 32; ++i) bm = fmaxf(bm, P.rel_bias[i * 8 + h] - b15);
;       mfix += bm * LOG2E;
;     }
;   }
;   if (MIXA) {
;     const int rel = tid - 192;
;     const float b15 = P.rel_bias[15 * 8 + h];
;     biasT[tid] = (P.rel_bias[t5_bucket(rel) * 8 + h] - b15) * LOG2E;
;   }
;   bf16x8 qf[NS];
; #pragma unroll
;   for (int s = 0; s < NS; ++s) qf[s] = *(const bf16x8*)(Qp + tokq * ldq + 16 * s + 8 * H);
;   const int nkt = 2 * qt + 2;
;   unsigned koff[NKI], voff[2];
; #pragma unroll
;   for (int i = 0; i < NKI; ++i) {
;     const int e = (w * NKI + i) * 64 + lane;
;     const int row = e / KCH, slot = e % KCH;
;     const int c = slot ^ (MIXA ? ((row >> 1) & 7) : ((row >> 2) & 3));
;     koff[i] = (unsigned)((row * ldk + c * 8) * 2);
;   }
; #pragma unroll
;   for (int i = 0; i < 2; ++i) {
;     const int e = (w * 2 + i) * 64 + lane;
;     const int row = e >> 3, slot = e & 7;
;     const int c = slot ^ ((row >> 1) & 7);
;     voff[i] = (unsigned)((row * S_ + c * 8) * 2);
;   }
;   unsigned mwn[2] = {0u, 0u};
;   auto issue_loads = [&](int kt) __attribute__((always_inline)) {
;     const char* kbp = (const char*)(Kp + (size_t)(kt * 64) * ldk);
;     const char* vbp = (const char*)(VT + kt * 64);
;     char* sk = smem + (kt & 1) * STG_B;
; #pragma unroll
;     for (int i = 0; i < NKI; ++i)
;       __builtin_amdgcn_global_load_lds((const unsigned*)(kbp + koff[i]), (unsigned*)(sk + (w * NKI + i) * 1024), 16, 0, 0);
; #pragma unroll
;     for (int i = 0; i < 2; ++i)
;       __builtin_amdgcn_global_load_lds((const unsigned*)(vbp + voff[i]), (unsigned*)(sk + KTILE_B + (w * 2 + i) * 1024), 16, 0, 0);
;     if (MIXA) {
;       if (kt <= cw) {
;         const unsigned* mp = mask + mask_base(b, cw) + (2 * kt) * 64 + (qpos & 63);
;         mwn[0] = mp[0]; mwn[1] = mp[64];
;       }
;     }
;   };
;   issue_loads(0);
;   f32x16 o[2];
; #pragma unroll
;   for (int d = 0; d < 2; ++d)
; #pragma unroll
;     for (int i = 0; i < 16; ++i) o[d][i] = 0.f;
;   float l = 0.f;
.LBB0_84:
	s_add_u32 s20, s65, s18
	s_addc_u32 s21, s66, s19
	global_load_dwordx4 v[4:7], v137, s[20:21] offset:32
	global_load_dwordx4 v[8:11], v137, s[20:21] offset:16
	global_load_dwordx4 v[12:15], v137, s[20:21]
	s_add_u32 s20, s67, s18
	s_addc_u32 s21, s68, s19
	global_load_dwordx4 v[16:19], v137, s[20:21]
	global_load_dwordx4 v[20:23], v137, s[20:21] offset:16
	global_load_dwordx4 v[24:27], v137, s[20:21] offset:32
	s_add_u32 s18, s18, 48
	s_addc_u32 s19, s19, 0
	s_cmpk_eq_i32 s18, 0x180
	s_waitcnt vmcnt(3)
	v_max3_f32 v2, v2, |v12|, |v13|
	s_waitcnt vmcnt(2)
	v_max3_f32 v1, v1, |v16|, |v17|
	v_max3_f32 v2, v2, |v14|, |v15|
	v_max3_f32 v1, v1, |v18|, |v19|
	v_max3_f32 v2, v2, |v8|, |v9|
	s_waitcnt vmcnt(1)
	v_max3_f32 v1, v1, |v20|, |v21|
	v_max3_f32 v2, v2, |v10|, |v11|
	v_max3_f32 v1, v1, |v22|, |v23|
	v_max3_f32 v2, v2, |v4|, |v5|
	s_waitcnt vmcnt(0)
	v_max3_f32 v1, v1, |v24|, |v25|
	v_max3_f32 v2, v2, |v6|, |v7|
	v_max3_f32 v1, v1, |v26|, |v27|
	s_cbranch_scc0 .LBB0_84
	v_lshl_or_b32 v3, v35, 3, s87
	v_ashrrev_i32_e32 v18, 6, v0
	v_mul_u32_u24_e32 v136, 0x300000, v3
	v_lshlrev_b32_e32 v3, 7, v34
	v_lshl_add_u32 v12, v18, 5, v3
	v_and_b32_e32 v20, 31, v0
	v_readlane_b32 s0, v252, 57
	v_or_b32_e32 v10, v12, v20
	v_lshlrev_b32_e32 v6, 14, v35
	v_readlane_b32 s1, v252, 58
	v_ashrrev_i32_e32 v11, 31, v10
	v_mov_b32_e32 v7, v137
	v_mul_f32_e32 v2, 0x42c3d70a, v2
	v_lshl_add_u64 v[8:9], s[0:1], 0, v[136:137]
	v_lshl_add_u64 v[112:113], v[10:11], 0, v[6:7]
	v_mul_f32_e32 v1, v1, v2
	v_mov_b64_e32 v[2:3], s[62:63]
	s_movk_i32 s0, 0x600
	v_bfe_u32 v139, v0, 5, 1
	v_mad_u64_u32 v[2:3], s[18:19], v112, s0, v[2:3]
	v_mad_i32_i24 v3, v113, s0, v3
	v_lshlrev_b32_e32 v6, 4, v139
	v_lshl_add_u64 v[2:3], v[2:3], 0, v[6:7]
	v_and_b32_e32 v21, 63, v0
	global_load_dwordx4 v[84:87], v[2:3], off
	global_load_dwordx4 v[80:83], v[2:3], off offset:32
	global_load_dwordx4 v[76:79], v[2:3], off offset:64
	global_load_dwordx4 v[72:75], v[2:3], off offset:96
	global_load_dwordx4 v[68:71], v[2:3], off offset:128
	global_load_dwordx4 v[64:67], v[2:3], off offset:160
	v_mul_lo_u32 v2, v18, s72
	v_or_b32_e32 v3, v2, v21
	s_mov_b32 s0, 0x2aaaaaab
	v_mul_hi_i32 v2, v3, s0
	v_lshrrev_b32_e32 v6, 31, v2
	v_ashrrev_i32_e32 v2, 1, v2
	v_add_u32_e32 v2, v2, v6
	v_mul_lo_u32 v6, v2, 12
	v_sub_u32_e32 v6, v3, v6
	v_lshrrev_b32_e32 v7, 2, v2
	v_bitop3_b32 v6, v7, v6, 3 bitop3:0x6c
	v_mul_lo_u32 v2, v2, s72
	v_lshl_add_u32 v2, v6, 4, v2
	v_add_u32_e32 v6, 64, v3
	v_mul_hi_i32 v7, v6, s0
	v_lshrrev_b32_e32 v10, 31, v7
	v_ashrrev_i32_e32 v7, 1, v7
	v_add_u32_e32 v7, v7, v10
	v_mul_lo_u32 v10, v7, 12
	v_sub_u32_e32 v6, v6, v10
	v_lshrrev_b32_e32 v10, 2, v7
	v_bitop3_b32 v6, v10, v6, 3 bitop3:0x6c
	v_mul_lo_u32 v7, v7, s72
	v_add_u32_e32 v3, 0x80, v3
	v_lshl_add_u32 v6, v6, 4, v7
	v_mul_hi_i32 v7, v3, s0
	v_lshrrev_b32_e32 v10, 31, v7
	v_ashrrev_i32_e32 v7, 1, v7
	v_add_u32_e32 v7, v7, v10
	v_mul_lo_u32 v10, v7, 12
	v_sub_u32_e32 v3, v3, v10
	v_lshrrev_b32_e32 v10, 2, v7
	v_bitop3_b32 v3, v10, v3, 3 bitop3:0x6c
	v_mul_lo_u32 v7, v7, s72
	v_lshl_add_u32 v10, v3, 4, v7
	v_mul_f32_e32 v114, 0x3e16c740, v1
	v_lshl_or_b32 v1, v18, 7, v21
	v_lshlrev_b32_e32 v3, 4, v0
	v_lshlrev_b32_e32 v7, 12, v1
	v_bitop3_b32 v22, v21, s92, v3 bitop3:0x48
	v_or_b32_e32 v1, 64, v1
	v_ashrrev_i32_e32 v127, 6, v12
	v_and_or_b32 v12, v7, s25, v22
	v_lshlrev_b32_e32 v7, 12, v1
	v_bitop3_b32 v1, v1, s92, v3 bitop3:0x48
	s_movk_i32 s0, 0x8000
	v_lshlrev_b32_e32 v19, 24, v35
	v_and_or_b32 v14, v7, s0, v1
	v_readlane_b32 s0, v252, 59
	v_or_b32_e32 v4, s88, v19
	v_mov_b32_e32 v5, v137
	v_readlane_b32 s1, v252, 60
	v_mov_b32_e32 v3, v137
	v_lshl_add_u64 v[16:17], v[8:9], 0, v[2:3]
	v_lshl_add_u64 v[4:5], s[0:1], 0, v[4:5]
	s_movk_i32 s0, 0xc00
	v_mul_lo_u32 v132, v18, s0
	v_add_u32_e32 v1, 0x400, v132
	v_readfirstlane_b32 s18, v132
	s_mov_b32 m0, s18
	v_mov_b32_e32 v7, v137
	v_readfirstlane_b32 s18, v1
	v_add_u32_e32 v1, 0x800, v132
	v_lshlrev_b32_e32 v135, 11, v18
	global_load_lds_dwordx4 v[16:17], off
	v_lshl_add_u64 v[16:17], v[8:9], 0, v[6:7]
	s_mov_b32 m0, s18
	v_mov_b32_e32 v11, v137
	v_readfirstlane_b32 s18, v1
	v_add_u32_e32 v1, 0x3000, v135
	global_load_lds_dwordx4 v[16:17], off
	v_lshl_add_u64 v[8:9], v[8:9], 0, v[10:11]
	s_mov_b32 m0, s18
	v_mov_b32_e32 v13, v137
	v_readfirstlane_b32 s18, v1
	v_add_u32_e32 v1, 0x3400, v135
	global_load_lds_dwordx4 v[8:9], off
	v_lshl_add_u64 v[8:9], v[4:5], 0, v[12:13]
	s_mov_b32 m0, s18
	v_mov_b32_e32 v15, v137
	v_readfirstlane_b32 s18, v1
	global_load_lds_dwordx4 v[8:9], off
	v_lshl_add_u64 v[4:5], v[4:5], 0, v[14:15]
	s_mov_b32 m0, s18
	v_and_b32_e32 v1, 19, v0
	global_load_lds_dwordx4 v[4:5], off
	v_lshlrev_b32_e32 v4, 1, v0
	v_lshrrev_b32_e32 v5, 1, v0
	v_and_b32_e32 v4, 8, v4
	v_and_b32_e32 v8, 4, v5
	v_or3_b32 v1, v4, v1, v8
	v_lshrrev_b32_e32 v4, 2, v1
	v_mul_u32_u24_e32 v141, 0xc0, v1
	v_or_b32_e32 v1, 2, v139
	v_bitop3_b32 v1, v4, v1, 3 bitop3:0x6c
	v_lshlrev_b32_e32 v142, 4, v1
	v_or_b32_e32 v1, 4, v139
	v_bitop3_b32 v1, v4, v1, 3 bitop3:0x6c
	v_lshlrev_b32_e32 v143, 4, v1
	v_or_b32_e32 v1, 6, v139
	v_bitop3_b32 v1, v4, v1, 3 bitop3:0x6c
	v_lshlrev_b32_e32 v144, 4, v1
	v_or_b32_e32 v1, 8, v139
	v_bitop3_b32 v1, v4, v1, 3 bitop3:0x6c
	v_lshlrev_b32_e32 v145, 4, v1
	v_or_b32_e32 v1, 10, v139
	v_bfe_u32 v0, v0, 1, 3
	v_bitop3_b32 v1, v4, v1, 3 bitop3:0x6c
	v_lshlrev_b32_e32 v146, 4, v1
	v_bitop3_b32 v1, v139, v0, 4 bitop3:0x36
	v_lshlrev_b32_e32 v130, 4, v1
	v_bitop3_b32 v1, v139, v5, 7 bitop3:0x78
	v_bitop3_b32 v8, v4, v139, 3 bitop3:0x6c
	v_lshlrev_b32_e32 v134, 4, v1
	v_bitop3_b32 v1, v139, v0, 2 bitop3:0x36
	v_bitop3_b32 v0, v139, v0, 6 bitop3:0x36
	v_lshlrev_b32_e32 v4, 12, v21
	s_waitcnt vmcnt(0)
; template <int DQK, bool MIXA, bool PIPE>
; DI void attn_item(const Params& P, int layer, char* smem, int b, int h, int qt) {
;     ...
;   issue_loads(0);
;   f32x16 o[2];
; #pragma unroll
;   for (int d = 0; d < 2; ++d)
; #pragma unroll
;     for (int i = 0; i < 16; ++i) o[d][i] = 0.f;
;   float l = 0.f;
;   const int pr = (l31 & ~12) | ((l31 & 4) << 1) | ((l31 & 8) >> 1);
;   const int swk = MIXA ? ((pr >> 1) & 7) : ((pr >> 2) & 3), swv = (l31 >> 1) & 7;
;   asm volatile("s_waitcnt vmcnt(0)" ::: "memory");
;   __syncthreads();
;   for (int kt = 0; kt < nkt; ++kt) {
;     unsigned mw[2] = {mwn[0], mwn[1]};
;     if (kt + 1 < nkt) issue_loads(kt + 1);
	v_lshlrev_b32_e32 v133, 4, v1
	v_lshlrev_b32_e32 v131, 4, v0
	v_or_b32_e32 v0, s86, v19
	v_mov_b32_e32 v1, v137
	s_mov_b64 s[18:19], 0x1d000080
	v_lshl_or_b32 v4, v18, 19, v4
	v_lshlrev_b32_e32 v128, 1, v34
	v_lshl_add_u64 v[0:1], v[0:1], 0, s[18:19]
	v_and_or_b32 v4, v4, s25, v22
	v_mov_b32_e32 v5, v137
	v_or_b32_e32 v136, 0x18003000, v136
	v_mov_b32_e32 v126, 0
	v_lshlrev_b32_e32 v129, 7, v20
	v_mov_b32_e32 v115, v114
	v_lshlrev_b32_e32 v140, 4, v8
	v_or_b32_e32 v147, 1, v128
	v_lshl_add_u64 v[116:117], v[0:1], 0, v[4:5]
	v_lshl_add_u64 v[118:119], v[0:1], 0, v[14:15]
	s_mov_b32 s22, 0
	v_lshl_add_u64 v[120:121], v[136:137], 0, v[2:3]
	v_lshl_add_u64 v[122:123], v[136:137], 0, v[6:7]
	v_lshl_add_u64 v[124:125], v[136:137], 0, v[10:11]
	s_mov_b64 s[44:45], 0
	v_mov_b32_e32 v0, 0
	v_mov_b32_e32 v1, v126
	v_mov_b32_e32 v2, v126
	v_mov_b32_e32 v3, v126
	v_mov_b32_e32 v4, v126
	v_mov_b32_e32 v5, v126
	v_mov_b32_e32 v6, v126
	v_mov_b32_e32 v7, v126
	v_mov_b32_e32 v8, v126
	v_mov_b32_e32 v9, v126
	v_mov_b32_e32 v10, v126
	v_mov_b32_e32 v11, v126
	v_mov_b32_e32 v12, v126
	v_mov_b32_e32 v13, v126
	v_mov_b32_e32 v14, v126
	v_mov_b32_e32 v15, v126
	v_mov_b32_e32 v16, v126
	v_mov_b32_e32 v17, v126
	v_mov_b32_e32 v18, v126
	v_mov_b32_e32 v19, v126
	v_mov_b32_e32 v20, v126
	v_mov_b32_e32 v21, v126
	v_mov_b32_e32 v22, v126
	v_mov_b32_e32 v23, v126
	v_mov_b32_e32 v24, v126
	v_mov_b32_e32 v25, v126
	v_mov_b32_e32 v26, v126
	v_mov_b32_e32 v27, v126
	v_mov_b32_e32 v28, v126
	v_mov_b32_e32 v29, v126
	v_mov_b32_e32 v30, v126
	v_mov_b32_e32 v31, v126
	s_waitcnt vmcnt(0) lgkmcnt(0)
	s_barrier
	v_readfirstlane_b32 s32, v132
	v_readfirstlane_b32 s73, v135
	s_mov_b64 s[36:37], s[74:75]
	s_mov_b64 s[38:39], s[74:75]
	s_branch .LBB0_87
.LBB0_86:
	s_or_b64 exec, exec, s[18:19]
	s_waitcnt vmcnt(0)
	v_cmp_eq_u32_e32 vcc, s20, v147
	s_add_u32 s38, s38, s94
	s_addc_u32 s39, s39, s95
	s_add_u32 s36, s36, s98
	s_addc_u32 s37, s37, s99
	s_or_b64 s[44:45], vcc, s[44:45]
	v_mov_b32_e32 v32, s21
	s_mov_b32 s22, s20
	s_waitcnt vmcnt(0) lgkmcnt(0)
	s_barrier
	s_andn2_b64 exec, exec, s[44:45]
	s_cbranch_execz .LBB0_89
; template <int DQK, bool MIXA, bool PIPE>
; DI void attn_item(const Params& P, int layer, char* smem, int b, int h, int qt) {
;     ...
;       __builtin_amdgcn_global_load_lds((const unsigned*)(kbp + koff[i]), (unsigned*)(sk + (w * NKI + i) * 1024), 16, 0, 0);
; #pragma unroll
;     for (int i = 0; i < 2; ++i)
;       __builtin_amdgcn_global_load_lds((const unsigned*)(vbp + voff[i]), (unsigned*)(sk + KTILE_B + (w * 2 + i) * 1024), 16, 0, 0);
;     ...
;       bf16x8 kf[2][NS];
; #pragma unroll
;       for (int kb = 0; kb < 2; ++kb)
; #pragma unroll
;         for (int s = 0; s < NS; ++s) kf[kb][s] = *(const bf16x8*)(Ks + (32 * kb + pr) * KROWB + (((2 * s + H) ^ swk) << 4));
;       __builtin_amdgcn_sched_barrier(0);
;       f32x16 sacc[2];
; #pragma unroll
;       for (int kb = 0; kb < 2; ++kb)
; #pragma unroll
;         for (int i = 0; i < 16; ++i) sacc[kb][i] = 0.f;
; #pragma unroll
;       for (int s = 0; s < NS; ++s) sacc[0] = __builtin_amdgcn_mfma_f32_32x32x16_bf16(kf[0][s], qf[s], sacc[0], 0, 0, 0);
;       bf16x8 vf[2][2][2];
; #pragma unroll
;       for (int d = 0; d < 2; ++d)
; #pragma unroll
;         for (int kb = 0; kb < 2; ++kb)
; #pragma unroll
;           for (int s2 = 0; s2 < 2; ++s2)
;             vf[d][kb][s2] = *(const bf16x8*)(Vs + (d * 32 + l31) * 128 + (((4 * kb + 2 * s2 + H) ^ swv) << 4));
;       __builtin_amdgcn_sched_barrier(0);
;       const bool near = MIXA && (kc >= cw - 2);
;       f32x2 ls2 = {0.f, 0.f};
;       const f32x2 sl2v = {sl2, sl2}, mfixv = {mfix, mfix};
;       unsigned pkw[2][2][4];
;       unsigned mrot[2];
; #pragma unroll
;       for (int kb = 0; kb < 2; ++kb) mrot[kb] = MIXA ? ((mw[kb] >> (8 * H)) << 8) : 0u;
;       auto chunk = [&](int kb, int c) __attribute__((always_inline)) {
;         const int s2 = 1 - (c >> 2), e = 3 - (c & 3);
;         const int r0 = 8 * s2 + 2 * e;
;         if (MIXA && c == 4) mrot[kb] <<= 8;
;         f32x2 xv2 = {sacc[kb][r0], sacc[kb][r0 + 1]};
;         xv2 = xv2 * sl2v - mfixv;
;         if (MIXA) {
;           if (near) {
;             const int kl = 16 * (r0 >> 3) + 8 * H + (r0 & 7);
;             const int rel = kc * 64 + 32 * kb + kl - qpos;
;             xv2.x += biasT[rel + 192];
;             xv2.y += biasT[rel + 193];
;           }
;         }
;         f32x2 p2 = {__builtin_amdgcn_exp2f(xv2.x), __builtin_amdgcn_exp2f(xv2.y)};
;         if (MIXA) {
;           float px = p2.x, py = p2.y;
.LBB0_87:
	s_add_i32 s20, s22, 1
	s_bitcmp1_b32 s20, 0
	s_cselect_b32 s21, 0x5000, 0
	s_add_u32 m0, s21, s32
	s_add_u32 s18, s21, s73
	global_load_lds_dwordx4 v120, s[36:37]
	s_add_u32 m0, m0, 0x400
	s_nop 0
	global_load_lds_dwordx4 v122, s[36:37]
	s_add_u32 m0, m0, 0x400
	s_nop 0
	global_load_lds_dwordx4 v124, s[36:37]
	s_add_u32 m0, s18, 0x3000
	v_cmp_le_i32_e32 vcc, s22, v127
	global_load_lds_dwordx4 v116, s[38:39]
	s_add_u32 m0, s18, 0x3400
	s_nop 0
	global_load_lds_dwordx4 v118, s[38:39]
	s_and_saveexec_b64 s[18:19], vcc
	s_cbranch_execz .LBB0_86
	s_bitcmp1_b32 s22, 0
	s_cselect_b32 s22, 0x5000, 0
	v_add_u32_e32 v32, s22, v141
	v_add_u32_e32 v36, v32, v140
	v_add_u32_e32 v44, v32, v142
	v_add_u32_e32 v48, v32, v143
	v_add_u32_e32 v49, v32, v144
	v_add_u32_e32 v50, v32, v145
	v_add_u32_e32 v51, v32, v146
	ds_read_b128 v[32:35], v36
	ds_read_b128 v[36:39], v36 offset:6144
	ds_read_b128 v[40:43], v44
	ds_read_b128 v[148:151], v44 offset:6144
	ds_read_b128 v[44:47], v48
	ds_read_b128 v[152:155], v48 offset:6144
	ds_read_b128 v[88:91], v49
	ds_read_b128 v[156:159], v49 offset:6144
	ds_read_b128 v[92:95], v50
	ds_read_b128 v[208:211], v50 offset:6144
	ds_read_b128 v[96:99], v51
	ds_read_b128 v[212:215], v51 offset:6144
	s_waitcnt lgkmcnt(0)
	v_mfma_f32_32x32x16_bf16 v[48:63], v[32:35], v[84:87], 0
	v_or_b32_e32 v32, s22, v129
	v_add_u32_e32 v33, v32, v134
	v_add_u32_e32 v34, v32, v133
	v_add_u32_e32 v35, v32, v130
	v_add_u32_e32 v32, v32, v131
	ds_read_b128 v[216:219], v33 offset:12288
	ds_read_b128 v[108:111], v34 offset:12288
	v_mfma_f32_32x32x16_bf16 v[48:63], v[40:43], v[80:83], v[48:63]
	v_mfma_f32_32x32x16_bf16 v[48:63], v[44:47], v[76:79], v[48:63]
	v_mfma_f32_32x32x16_bf16 v[48:63], v[88:91], v[72:75], v[48:63]
	ds_read_b128 v[88:91], v35 offset:12288
	v_mfma_f32_32x32x16_bf16 v[48:63], v[92:95], v[68:71], v[48:63]
	v_mfma_f32_32x32x16_bf16 v[48:63], v[96:99], v[64:67], v[48:63]
	ds_read_b128 v[92:95], v32 offset:12288
	ds_read_b128 v[220:223], v33 offset:16384
	ds_read_b128 v[104:107], v34 offset:16384
	ds_read_b128 v[100:103], v35 offset:16384
	ds_read_b128 v[96:99], v32 offset:16384
	s_nop 6
	v_pk_fma_f32 v[32:33], v[62:63], s[96:97], v[114:115] op_sel_hi:[1,0,1] neg_lo:[0,0,1] neg_hi:[0,0,1]
	s_nop 0
	v_exp_f32_e32 v32, v32
	v_exp_f32_e32 v33, v33
	s_nop 0
	v_pk_add_f32 v[224:225], v[32:33], 0 op_sel_hi:[1,0]
	v_cvt_pk_bf16_f32 v63, v32, v33
	v_mfma_f32_32x32x16_bf16 v[32:47], v[36:39], v[84:87], 0
	v_fma_f32 v60, v60, s96, -v114
	v_fma_f32 v61, v61, s96, -v115
	v_mfma_f32_32x32x16_bf16 v[32:47], v[148:151], v[80:83], v[32:47]
	v_exp_f32_e32 v60, v60
	v_exp_f32_e32 v61, v61
	s_nop 0
	v_pk_add_f32 v[224:225], v[60:61], v[224:225]
	v_cvt_pk_bf16_f32 v62, v60, v61
	v_pk_fma_f32 v[58:59], v[58:59], s[96:97], v[114:115] op_sel_hi:[1,0,1] neg_lo:[0,0,1] neg_hi:[0,0,1]
	v_pk_fma_f32 v[56:57], v[56:57], s[96:97], v[114:115] op_sel_hi:[1,0,1] neg_lo:[0,0,1] neg_hi:[0,0,1]
	v_exp_f32_e32 v58, v58
	v_exp_f32_e32 v59, v59
	v_exp_f32_e32 v56, v56
	v_exp_f32_e32 v57, v57
	v_mfma_f32_32x32x16_bf16 v[32:47], v[152:155], v[76:79], v[32:47]
	v_add_f32_e64 v148, v58, v224
	v_add_f32_e64 v149, v59, v225
	v_cvt_pk_bf16_f32 v61, v58, v59
	v_add_f32_e64 v58, v56, v148
	v_add_f32_e64 v59, v57, v149
	v_cvt_pk_bf16_f32 v60, v56, v57
	v_pk_fma_f32 v[54:55], v[54:55], s[96:97], v[114:115] op_sel_hi:[1,0,1] neg_lo:[0,0,1] neg_hi:[0,0,1]
	v_mfma_f32_32x32x16_bf16 v[32:47], v[156:159], v[72:75], v[32:47]
	v_exp_f32_e32 v54, v54
	v_exp_f32_e32 v55, v55
	s_nop 0
	v_pk_add_f32 v[56:57], v[54:55], v[58:59]
	v_cvt_pk_bf16_f32 v55, v54, v55
	v_pk_fma_f32 v[52:53], v[52:53], s[96:97], v[114:115] op_sel_hi:[1,0,1] neg_lo:[0,0,1] neg_hi:[0,0,1]
	v_mfma_f32_32x32x16_bf16 v[32:47], v[208:211], v[68:71], v[32:47]
	v_exp_f32_e32 v52, v52
	v_exp_f32_e32 v53, v53
	s_nop 0
	v_pk_add_f32 v[56:57], v[52:53], v[56:57]
	v_cvt_pk_bf16_f32 v54, v52, v53
	v_pk_fma_f32 v[50:51], v[50:51], s[96:97], v[114:115] op_sel_hi:[1,0,1] neg_lo:[0,0,1] neg_hi:[0,0,1]
	v_pk_fma_f32 v[48:49], v[48:49], s[96:97], v[114:115] op_sel_hi:[1,0,1] neg_lo:[0,0,1] neg_hi:[0,0,1]
	v_exp_f32_e32 v50, v50
	v_exp_f32_e32 v51, v51
	v_exp_f32_e32 v48, v48
	v_exp_f32_e32 v49, v49
	v_mfma_f32_32x32x16_bf16 v[32:47], v[212:215], v[64:67], v[32:47]
	v_add_f32_e64 v56, v50, v56
	v_add_f32_e64 v57, v51, v57
	v_cvt_pk_bf16_f32 v53, v50, v51
	v_cvt_pk_bf16_f32 v52, v48, v49
	v_add_f32_e64 v48, v48, v56
	v_add_f32_e64 v49, v49, v57
	s_waitcnt lgkmcnt(0)
	v_mfma_f32_32x32x16_bf16 v[0:15], v[216:219], v[52:55], v[0:15]
	s_nop 3
	v_fma_f32 v46, v46, s96, -v114
	v_fma_f32 v47, v47, s96, -v115
	v_fma_f32 v44, v44, s96, -v114
	v_fma_f32 v45, v45, s96, -v115
	v_exp_f32_e32 v46, v46
	v_exp_f32_e32 v47, v47
	v_exp_f32_e32 v44, v44
	v_exp_f32_e32 v45, v45
	v_pk_add_f32 v[48:49], v[48:49], v[46:47]
	v_cvt_pk_bf16_f32 v47, v46, v47
	v_pk_add_f32 v[48:49], v[44:45], v[48:49]
	v_cvt_pk_bf16_f32 v46, v44, v45
	v_mfma_f32_32x32x16_bf16 v[16:31], v[220:223], v[52:55], v[16:31]
	v_fma_f32 v42, v42, s96, -v114
	v_fma_f32 v43, v43, s96, -v115
	v_fma_f32 v40, v40, s96, -v114
	v_fma_f32 v41, v41, s96, -v115
	v_exp_f32_e32 v42, v42
	v_exp_f32_e32 v43, v43
	v_exp_f32_e32 v40, v40
	v_exp_f32_e32 v41, v41
	v_pk_add_f32 v[48:49], v[42:43], v[48:49]
	v_cvt_pk_bf16_f32 v45, v42, v43
	v_pk_add_f32 v[42:43], v[40:41], v[48:49]
	v_cvt_pk_bf16_f32 v44, v40, v41
	v_mfma_f32_32x32x16_bf16 v[0:15], v[108:111], v[60:63], v[0:15]
	v_fma_f32 v38, v38, s96, -v114
	v_fma_f32 v39, v39, s96, -v115
	v_fma_f32 v36, v36, s96, -v114
	v_fma_f32 v37, v37, s96, -v115
	v_exp_f32_e32 v38, v38
	v_exp_f32_e32 v39, v39
	v_exp_f32_e32 v36, v36
	v_exp_f32_e32 v37, v37
	v_pk_add_f32 v[40:41], v[38:39], v[42:43]
	v_cvt_pk_bf16_f32 v39, v38, v39
	v_pk_add_f32 v[40:41], v[36:37], v[40:41]
	v_cvt_pk_bf16_f32 v38, v36, v37
	v_mfma_f32_32x32x16_bf16 v[16:31], v[104:107], v[60:63], v[16:31]
	v_fma_f32 v34, v34, s96, -v114
	v_fma_f32 v35, v35, s96, -v115
	v_fma_f32 v32, v32, s96, -v114
	v_fma_f32 v33, v33, s96, -v115
	v_exp_f32_e32 v34, v34
	v_exp_f32_e32 v35, v35
	v_exp_f32_e32 v32, v32
	v_exp_f32_e32 v33, v33
	v_cvt_pk_bf16_f32 v37, v34, v35
	v_cvt_pk_bf16_f32 v36, v32, v33
	s_nop 1
	v_mfma_f32_32x32x16_bf16 v[0:15], v[88:91], v[36:39], v[0:15]
	v_add_f32_e64 v34, v34, v40
	v_add_f32_e64 v35, v35, v41
	v_add_f32_e64 v32, v32, v34
	v_add_f32_e64 v33, v33, v35
	v_add_f32_e32 v32, v32, v33
	v_add_f32_e32 v126, v126, v32
	v_mfma_f32_32x32x16_bf16 v[16:31], v[100:103], v[36:39], v[16:31]
	v_mfma_f32_32x32x16_bf16 v[0:15], v[92:95], v[44:47], v[0:15]
	v_mfma_f32_32x32x16_bf16 v[16:31], v[96:99], v[44:47], v[16:31]
	s_branch .LBB0_86

; template <int DQK, bool MIXA, bool PIPE>
; DI void attn_item(const Params& P, int layer, char* smem, int b, int h, int qt) {
;     ...
;     if (MIXA) {
;       const float b15 = P.rel_bias[15 * 8 + h];
;       float bm = 0.f;
;       for (int i = 0; i < 32; ++i) bm = fmaxf(bm, P.rel_bias[i * 8 + h] - b15);
;       mfix += bm * LOG2E;
;     }
;   }
;   if (MIXA) {
;     const int rel = tid - 192;
;     const float b15 = P.rel_bias[15 * 8 + h];
;     biasT[tid] = (P.rel_bias[t5_bucket(rel) * 8 + h] - b15) * LOG2E;
;   }
;   bf16x8 qf[NS];
; #pragma unroll
;   for (int s = 0; s < NS; ++s) qf[s] = *(const bf16x8*)(Qp + tokq * ldq + 16 * s + 8 * H);
;   const int nkt = 2 * qt + 2;
;   unsigned koff[NKI], voff[2];
; #pragma unroll
;   for (int i = 0; i < NKI; ++i) {
;     const int e = (w * NKI + i) * 64 + lane;
;     const int row = e / KCH, slot = e % KCH;
;     const int c = slot ^ (MIXA ? ((row >> 1) & 7) : ((row >> 2) & 3));
;     koff[i] = (unsigned)((row * ldk + c * 8) * 2);
;   }
; #pragma unroll
;   for (int i = 0; i < 2; ++i) {
;     const int e = (w * 2 + i) * 64 + lane;
;     const int row = e >> 3, slot = e & 7;
;     const int c = slot ^ ((row >> 1) & 7);
;     voff[i] = (unsigned)((row * S_ + c * 8) * 2);
;   }
;   unsigned mwn[2] = {0u, 0u};
;   auto issue_loads = [&](int kt) __attribute__((always_inline)) {
;     const char* kbp = (const char*)(Kp + (size_t)(kt * 64) * ldk);
;     const char* vbp = (const char*)(VT + kt * 64);
;     char* sk = smem + (kt & 1) * STG_B;
; #pragma unroll
;     for (int i = 0; i < NKI; ++i)
;       __builtin_amdgcn_global_load_lds((const unsigned*)(kbp + koff[i]), (unsigned*)(sk + (w * NKI + i) * 1024), 16, 0, 0);
; #pragma unroll
;     for (int i = 0; i < 2; ++i)
;       __builtin_amdgcn_global_load_lds((const unsigned*)(vbp + voff[i]), (unsigned*)(sk + KTILE_B + (w * 2 + i) * 1024), 16, 0, 0);
;     if (MIXA) {
;       if (kt <= cw) {
;         const unsigned* mp = mask + mask_base(b, cw) + (2 * kt) * 64 + (qpos & 63);
;         mwn[0] = mp[0]; mwn[1] = mp[64];
;       }
;     }
;   };
;   issue_loads(0);
;   f32x16 o[2];
; #pragma unroll
;   for (int d = 0; d < 2; ++d)
; #pragma unroll
;     for (int i = 0; i < 16; ++i) o[d][i] = 0.f;
;   float l = 0.f;
;   const int pr = (l31 & ~12) | ((l31 & 4) << 1) | ((l31 & 8) >> 1);
;   const int swk = MIXA ? ((pr >> 1) & 7) : ((pr >> 2) & 3), swv = (l31 >> 1) & 7;
.LBB0_107:
	s_or_b64 exec, exec, s[18:19]
	v_mad_u64_u32 v[126:127], s[18:19], v0, s33, 0
	v_mul_f32_e32 v0, 0x42828f5c, v12
	v_mad_i32_i24 v127, v1, s33, v127
	v_mul_f32_e32 v0, v11, v0
	v_sub_f32_e32 v1, v47, v13
	v_sub_f32_e32 v11, v48, v13
	v_max3_f32 v1, v1, 0, v11
	v_sub_f32_e32 v11, v44, v13
	v_sub_f32_e32 v12, v45, v13
	v_max3_f32 v1, v1, v11, v12
	v_sub_f32_e32 v11, v42, v13
	v_sub_f32_e32 v12, v43, v13
	v_max3_f32 v1, v1, v11, v12
	v_sub_f32_e32 v11, v38, v13
	v_sub_f32_e32 v12, v39, v13
	v_max3_f32 v1, v1, v11, v12
	v_sub_f32_e32 v11, v40, v13
	v_sub_f32_e32 v12, v41, v13
	v_max3_f32 v1, v1, v11, v12
	v_sub_f32_e32 v11, v36, v13
	v_sub_f32_e32 v12, v37, v13
	v_max3_f32 v1, v1, v11, v12
	v_sub_f32_e32 v11, v32, v13
	v_sub_f32_e32 v12, v33, v13
	v_max3_f32 v1, v1, v11, v12
	v_sub_f32_e32 v11, v31, v13
	v_sub_f32_e32 v12, v13, v13
	v_max3_f32 v1, v1, v11, v12
	v_sub_f32_e32 v11, v28, v13
	v_sub_f32_e32 v12, v29, v13
	v_max3_f32 v1, v1, v11, v12
	v_sub_f32_e32 v11, v26, v13
	v_sub_f32_e32 v12, v27, v13
	v_max3_f32 v1, v1, v11, v12
	v_sub_f32_e32 v11, v24, v13
	v_sub_f32_e32 v12, v25, v13
	v_max3_f32 v1, v1, v11, v12
	v_sub_f32_e32 v11, v22, v13
	v_sub_f32_e32 v12, v23, v13
	v_max3_f32 v1, v1, v11, v12
	v_sub_f32_e32 v11, v20, v13
	v_sub_f32_e32 v12, v21, v13
	v_max3_f32 v1, v1, v11, v12
	v_sub_f32_e32 v11, v18, v13
	v_sub_f32_e32 v12, v19, v13
	v_max3_f32 v1, v1, v11, v12
	v_sub_f32_e32 v11, v16, v13
	v_sub_f32_e32 v12, v17, v13
	v_max3_f32 v1, v1, v11, v12
	v_sub_f32_e32 v11, v14, v13
	v_sub_f32_e32 v12, v15, v13
	v_max3_f32 v1, v1, v11, v12
	v_mul_f32_e32 v128, 0x3fb8aa3b, v1
	v_lshlrev_b32_e32 v1, 1, v10
	v_lshrrev_b32_e32 v11, 1, v10
	v_fmac_f32_e32 v128, 0x3e38aa3b, v0
	v_and_b32_e32 v0, 19, v10
	v_and_b32_e32 v1, 8, v1
	v_and_b32_e32 v12, 4, v11
	v_or3_b32 v0, v1, v0, v12
	v_lshrrev_b32_e32 v1, 1, v0
	v_lshlrev_b32_e32 v155, 7, v0
	v_bitop3_b32 v0, v1, v139, 7 bitop3:0x6c
	v_lshlrev_b32_e32 v157, 4, v0
	v_or_b32_e32 v0, 2, v139
	v_bitop3_b32 v0, v1, v0, 7 bitop3:0x6c
	v_lshlrev_b32_e32 v158, 4, v0
	v_or_b32_e32 v0, 4, v139
	v_bitop3_b32 v0, v1, v0, 7 bitop3:0x6c
	v_lshlrev_b32_e32 v159, 4, v0
	v_or_b32_e32 v0, 6, v139
	v_bfe_u32 v10, v10, 1, 3
	v_bitop3_b32 v0, v1, v0, 7 bitop3:0x6c
	v_lshlrev_b32_e32 v160, 4, v0
	v_bitop3_b32 v0, v139, v10, 4 bitop3:0x36
	v_lshlrev_b32_e32 v151, 4, v0
	v_bitop3_b32 v0, v139, v11, 7 bitop3:0x78
	v_lshlrev_b32_e32 v154, 4, v0
	v_bitop3_b32 v0, v139, v10, 2 bitop3:0x36
	v_lshlrev_b32_e32 v153, 4, v0
	v_bitop3_b32 v0, v139, v10, 6 bitop3:0x36
	v_lshlrev_b32_e32 v152, 4, v0
	v_lshlrev_b32_e32 v0, 5, v139
	v_add_lshl_u32 v1, v50, v51, 2
	v_sub_u32_e32 v0, v0, v1
	v_add_u32_e32 v162, 0xa300, v0
	v_lshlrev_b64 v[0:1], 2, v[6:7]
	v_lshlrev_b32_e32 v6, 12, v49
	v_lshl_add_u64 v[130:131], v[8:9], 2, v[0:1]
	v_add_u32_e32 v0, s86, v46
	v_mov_b32_e32 v1, v137
	s_mov_b64 s[18:19], 0x1b000080
	v_lshl_or_b32 v6, v30, 19, v6
	v_lshl_add_u64 v[0:1], v[0:1], 0, s[18:19]
	v_and_or_b32 v6, v6, s25, v54
	v_mov_b32_e32 v7, v137
	v_lshl_add_u64 v[132:133], v[0:1], 0, v[6:7]
	v_add_u32_e32 v6, v52, v49
	v_mov_b32_e32 v7, 0x40000
	v_lshl_add_u32 v6, v6, 12, v7
	s_movk_i32 s0, 0x8000
	v_and_or_b32 v6, v6, s0, v53
	v_readlane_b32 s0, v253, 17
	s_waitcnt vmcnt(0)
	v_mov_b32_e32 v7, v137
	v_readlane_b32 s1, v253, 18
	v_mov_b32_e32 v125, 0
	v_lshl_add_u64 v[134:135], v[0:1], 0, v[6:7]
	v_lshl_add_u64 v[0:1], s[0:1], 0, v[136:137]
	v_lshlrev_b32_e32 v147, 3, v139
	v_lshlrev_b32_e32 v150, 7, v51
	v_add_u32_e32 v148, -2, v145
	v_mov_b32_e32 v129, v128
	v_lshl_or_b32 v149, v34, 1, 1
	v_lshl_add_u64 v[140:141], v[0:1], 0, v[2:3]
	v_lshl_add_u64 v[142:143], v[0:1], 0, v[4:5]
	s_mov_b32 s22, 0
	s_mov_b64 s[58:59], 0
	v_mov_b32_e32 v0, 0
	v_mov_b32_e32 v1, v125
	v_mov_b32_e32 v2, v125
	v_mov_b32_e32 v3, v125
	v_mov_b32_e32 v4, v125
	v_mov_b32_e32 v5, v125
	v_mov_b32_e32 v6, v125
	v_mov_b32_e32 v7, v125
	v_mov_b32_e32 v8, v125
	v_mov_b32_e32 v9, v125
	v_mov_b32_e32 v10, v125
	v_mov_b32_e32 v11, v125
	v_mov_b32_e32 v12, v125
	v_mov_b32_e32 v13, v125
	v_mov_b32_e32 v14, v125
	v_mov_b32_e32 v15, v125
	v_mov_b32_e32 v16, v125
	v_mov_b32_e32 v17, v125
	v_mov_b32_e32 v18, v125
	v_mov_b32_e32 v19, v125
	v_mov_b32_e32 v20, v125
	v_mov_b32_e32 v21, v125
	v_mov_b32_e32 v22, v125
	v_mov_b32_e32 v23, v125
	v_mov_b32_e32 v24, v125
	v_mov_b32_e32 v25, v125
	v_mov_b32_e32 v26, v125
	v_mov_b32_e32 v27, v125
	v_mov_b32_e32 v28, v125
	v_mov_b32_e32 v29, v125
	v_mov_b32_e32 v30, v125
	v_mov_b32_e32 v31, v125
	s_waitcnt vmcnt(0)
	v_mov_b32_e32 v136, v164
	v_mov_b32_e32 v156, v166
	s_waitcnt lgkmcnt(0)
	s_barrier
	v_readfirstlane_b32 s32, v146
	s_mov_b64 s[36:37], s[74:75]
	s_mov_b64 s[38:39], s[74:75]
	s_add_u32 s76, s74, 0x7f00000
	s_addc_u32 s77, s75, 0
	s_branch .LBB0_110

; template <int DQK, bool MIXA, bool PIPE>
; DI void attn_item(const Params& P, int layer, char* smem, int b, int h, int qt) {
;     ...
;   auto issue_loads = [&](int kt) __attribute__((always_inline)) {
;     const char* kbp = (const char*)(Kp + (size_t)(kt * 64) * ldk);
;     const char* vbp = (const char*)(VT + kt * 64);
;     char* sk = smem + (kt & 1) * STG_B;
; #pragma unroll
;     for (int i = 0; i < NKI; ++i)
;       __builtin_amdgcn_global_load_lds((const unsigned*)(kbp + koff[i]), (unsigned*)(sk + (w * NKI + i) * 1024), 16, 0, 0);
; #pragma unroll
;     for (int i = 0; i < 2; ++i)
;       __builtin_amdgcn_global_load_lds((const unsigned*)(vbp + voff[i]), (unsigned*)(sk + KTILE_B + (w * 2 + i) * 1024), 16, 0, 0);
;     if (MIXA) {
;       if (kt <= cw) {
;         const unsigned* mp = mask + mask_base(b, cw) + (2 * kt) * 64 + (qpos & 63);
;         mwn[0] = mp[0]; mwn[1] = mp[64];
;       }
;     }
;   };
;   issue_loads(0);
;   f32x16 o[2];
; #pragma unroll
;   for (int d = 0; d < 2; ++d)
; #pragma unroll
;     for (int i = 0; i < 16; ++i) o[d][i] = 0.f;
;   float l = 0.f;
;   const int pr = (l31 & ~12) | ((l31 & 4) << 1) | ((l31 & 8) >> 1);
;   const int swk = MIXA ? ((pr >> 1) & 7) : ((pr >> 2) & 3), swv = (l31 >> 1) & 7;
;   asm volatile("s_waitcnt vmcnt(0)" ::: "memory");
;   __syncthreads();
;   for (int kt = 0; kt < nkt; ++kt) {
;     unsigned mw[2] = {mwn[0], mwn[1]};
;     if (kt + 1 < nkt) issue_loads(kt + 1);
.LBB0_109:
	s_or_b64 exec, exec, s[60:61]
	v_cmp_eq_u32_e32 vcc, s20, v149
	s_waitcnt vmcnt(0)
	s_or_b64 s[58:59], vcc, s[58:59]
	s_mov_b64 s[0:1], 0x58000
	s_andn2_b64 s[18:19], s[56:57], exec
	s_and_b64 s[22:23], s[42:43], exec
	v_add_u32_e32 v162, 0x100, v162
	s_add_u32 s76, s76, s30
	s_addc_u32 s77, s77, s31
	s_add_u32 s38, s38, s94
	s_addc_u32 s39, s39, s95
	s_add_u32 s36, s36, s0
	s_addc_u32 s37, s37, s1
	v_mov_b32_e32 v36, s21
	s_or_b64 s[56:57], s[18:19], s[22:23]
	s_mov_b32 s22, s20
	s_waitcnt vmcnt(0)
	v_mov_b32_e32 v166, v156
	v_mov_b32_e32 v164, v136
	s_waitcnt lgkmcnt(0)
	s_barrier
	s_andn2_b64 exec, exec, s[58:59]
	s_cbranch_execz .LBB0_145
.LBB0_110:
	s_add_i32 s20, s22, 1
	s_bitcmp1_b32 s20, 0
	s_cselect_b32 s21, 0x5000, 0
	s_add_u32 m0, s21, s32
	v_cmp_lt_i32_e64 s[42:43], s22, v145
	global_load_lds_dwordx4 v140, s[36:37]
	s_add_u32 m0, m0, 0x400
	s_nop 0
	global_load_lds_dwordx4 v142, s[36:37]
	s_add_u32 m0, m0, 0x1c00
	s_nop 0
	global_load_lds_dwordx4 v132, s[38:39]
	s_add_u32 m0, m0, 0x400
	s_nop 0
	global_load_lds_dwordx4 v134, s[38:39]
	s_and_saveexec_b64 s[18:19], s[42:43]
	s_cbranch_execz .LBB0_112
	global_load_dword v156, v130, s[76:77] offset:512
	global_load_dword v136, v130, s[76:77] offset:768

; DI int ltid() { int t = threadIdx.x; asm volatile("" : "+v"(t)); return t; }
; DI void phase_rmsnorm(const float* x, const float* g, bf16* hn) {
;   const int lane = ltid() & 63, w = ltid() >> 6;
;   for (int t = blockIdx.x * 4 + w; t < T_; t += gridDim.x * 4) {
;     const float4* xr = (const float4*)(x + (size_t)t * DM);
;     float4 v[4];
;     float ss = 0.f;
; #pragma unroll
;     for (int i = 0; i < 4; ++i) {
;       v[i] = xr[lane + 64 * i];
;       ss += v[i].x * v[i].x + v[i].y * v[i].y + v[i].z * v[i].z + v[i].w * v[i].w;
;     }
;     ss = wave_sum(ss);
;     const float r = rsqrtf(ss * (1.f / DM) + EPS);
.LBB0_178:
	s_movk_i32 s73, 0x180
	s_movk_i32 s76, 0x7bf
	s_movk_i32 s77, 0xc1
	v_mov_b32_e32 v1, v161
	v_mov_b32_e32 v0, v161
	v_readlane_b32 s0, v252, 50
	v_ashrrev_i32_e32 v0, 6, v0
	s_nop 0
	v_add_u32_e32 v0, s0, v0
	s_mov_b32 s0, 0x8000
	v_cmp_gt_i32_e32 vcc, s0, v0
	s_and_saveexec_b64 s[0:1], vcc
	v_readlane_b32 s84, v254, 56
	v_readlane_b32 s18, v255, 3
	v_readlane_b32 s85, v254, 57
	v_readlane_b32 s26, v254, 60
	s_mov_b32 s2, 0x800000
	s_movk_i32 s3, 0x7fff
	v_readlane_b32 s19, v255, 4
	s_cbranch_execz .LBB0_181
	v_and_b32_e32 v2, 64, v180
	v_add_u32_e32 v2, 64, v2
	v_xor_b32_e32 v3, 32, v180
	v_cmp_lt_i32_e32 vcc, v3, v2
	v_readlane_b32 s4, v254, 63
	s_lshl_b32 s10, s4, 10
	v_cndmask_b32_e32 v3, v180, v3, vcc
	v_lshlrev_b32_e32 v12, 2, v3
	v_xor_b32_e32 v3, 16, v180
	v_cmp_lt_i32_e32 vcc, v3, v2
	s_ashr_i32 s11, s10, 31
	v_readlane_b32 s40, v252, 16
	v_cndmask_b32_e32 v3, v180, v3, vcc
	v_lshlrev_b32_e32 v13, 2, v3
	v_xor_b32_e32 v3, 8, v180
	v_cmp_lt_i32_e32 vcc, v3, v2
	s_lshl_b64 s[10:11], s[10:11], 2
	v_readlane_b32 s44, v252, 20
	v_cndmask_b32_e32 v3, v180, v3, vcc
	v_lshlrev_b32_e32 v14, 2, v3
	v_xor_b32_e32 v3, 4, v180
	v_cmp_lt_i32_e32 vcc, v3, v2
	v_and_b32_e32 v1, 63, v1
	v_readlane_b32 s45, v252, 21
	v_cndmask_b32_e32 v3, v180, v3, vcc
	v_lshlrev_b32_e32 v15, 2, v3
	v_xor_b32_e32 v3, 2, v180
	v_cmp_lt_i32_e32 vcc, v3, v2
	s_add_u32 s10, s44, s10
	v_lshlrev_b32_e32 v6, 2, v1
	v_cndmask_b32_e32 v3, v180, v3, vcc
	v_lshlrev_b32_e32 v16, 2, v3
	v_xor_b32_e32 v3, 1, v180
	v_cmp_lt_i32_e32 vcc, v3, v2
	s_addc_u32 s11, s45, s11
	v_lshlrev_b32_e32 v136, 4, v1
	v_cndmask_b32_e32 v2, v180, v3, vcc
	v_or_b32_e32 v8, 0x100, v6
	v_or_b32_e32 v10, 0x200, v6
	v_or_b32_e32 v18, 0x300, v6
	v_lshlrev_b32_e32 v17, 2, v2
	v_lshl_add_u64 v[2:3], s[10:11], 0, v[136:137]
	v_lshl_add_u64 v[4:5], s[18:19], 0, v[136:137]
	s_mov_b64 s[10:11], 0
	v_lshlrev_b32_e32 v136, 1, v6
	v_lshlrev_b32_e32 v6, 1, v8
	v_lshlrev_b32_e32 v8, 1, v10
	v_lshlrev_b32_e32 v10, 1, v18
	v_readlane_b32 s41, v252, 17
	v_readlane_b32 s42, v252, 18
	v_readlane_b32 s43, v252, 19
	v_readlane_b32 s46, v252, 22
	v_readlane_b32 s47, v252, 23
	v_readlane_b32 s48, v252, 24
	v_readlane_b32 s49, v252, 25
	v_readlane_b32 s50, v252, 26
	v_readlane_b32 s51, v252, 27
	v_readlane_b32 s52, v252, 28
	v_readlane_b32 s53, v252, 29
	v_readlane_b32 s54, v252, 30
	v_readlane_b32 s55, v252, 31
